# grid barriers: L1 invalidate issued right behind the arrival atomic (counted wait vmcnt(1)), overlapping the leader's L2 write-back
# baseline (speedup 1.0000x reference)
.Lgs_census_done:
	v_min_u32_e32 v18, 1, v1
	v_min_u32_e32 v22, 1, v2
	v_add_u32_e32 v18, v18, v22
	v_min_u32_e32 v22, 1, v3
	v_add_u32_e32 v18, v18, v22
	v_min_u32_e32 v22, 1, v4
	v_add_u32_e32 v18, v18, v22
	v_min_u32_e32 v22, 1, v5
	v_add_u32_e32 v18, v18, v22
	v_min_u32_e32 v22, 1, v6
	v_add_u32_e32 v18, v18, v22
	v_min_u32_e32 v22, 1, v7
	v_add_u32_e32 v18, v18, v22
	v_min_u32_e32 v22, 1, v8
	v_add_u32_e32 v18, v18, v22
	v_min_u32_e32 v22, 1, v9
	v_add_u32_e32 v18, v18, v22
	v_min_u32_e32 v22, 1, v10
	v_add_u32_e32 v18, v18, v22
	v_min_u32_e32 v22, 1, v11
	v_add_u32_e32 v18, v18, v22
	v_min_u32_e32 v22, 1, v12
	v_add_u32_e32 v18, v18, v22
	v_min_u32_e32 v22, 1, v13
	v_add_u32_e32 v18, v18, v22
	v_min_u32_e32 v22, 1, v14
	v_add_u32_e32 v18, v18, v22
	v_min_u32_e32 v22, 1, v15
	v_add_u32_e32 v18, v18, v22
	v_min_u32_e32 v22, 1, v16
	v_add_u32_e32 v18, v18, v22
	v_max_u32_e32 v19, 1, v19
	v_max_u32_e32 v18, 1, v18
	v_mov_b32_e32 v22, 0x20ff0
	ds_write_b32 v22, v19
	v_mov_b32_e32 v22, 0x20ff4
	ds_write_b32 v22, v18
	s_waitcnt lgkmcnt(0)
	v_readlane_b32 s98, v248, 1
	v_readlane_b32 s99, v248, 2
	v_mov_b32_e32 v0, 0x20ff0
	ds_read2_b32 v[2:3], v0 offset1:1
	v_mov_b32_e32 v1, 1
	v_mov_b32_e32 v4, s97
	v_lshlrev_b32_e32 v4, 8, v4
	s_add_u32 s98, s98, 0x1000
	s_addc_u32 s99, s99, 0
	s_nop 2
	global_atomic_add v5, v4, v1, s[98:99] offset:1024 sc0
	buffer_inv sc1
	s_waitcnt vmcnt(1) lgkmcnt(0)
	v_mul_u32_u24_e32 v2, 1, v2
	v_mul_u32_u24_e32 v3, 1, v3
	v_add_u32_e32 v5, 1, v5
	v_cmp_ne_u32_e32 vcc, v5, v2
	v_mov_b32_e32 v6, 0x2400
	s_cbranch_vccnz .Lxb0_poll
	buffer_wbl2 sc1
	s_waitcnt vmcnt(0)
	global_atomic_add v6, v1, s[98:99]

.Lxb0_poll:

	s_mov_b32 s100, 0

.LBB0_172:
	s_waitcnt vmcnt(0)
	s_barrier
	s_mov_b64 s[0:1], exec
	v_readlane_b32 s2, v248, 3
	v_readlane_b32 s3, v248, 4
	s_and_b64 s[2:3], s[0:1], s[2:3]
	s_mov_b64 exec, s[2:3]
	s_cbranch_execz .LBB0_224
	v_readlane_b32 s98, v248, 1
	v_readlane_b32 s99, v248, 2
	v_mov_b32_e32 v0, 0x20ff0
	ds_read2_b32 v[2:3], v0 offset1:1
	v_mov_b32_e32 v1, 1
	v_mov_b32_e32 v4, s97
	v_lshlrev_b32_e32 v4, 8, v4
	s_add_u32 s98, s98, 0x1000
	s_addc_u32 s99, s99, 0
	s_nop 2
	global_atomic_add v5, v4, v1, s[98:99] offset:1024 sc0
	buffer_inv sc1
	s_waitcnt vmcnt(1) lgkmcnt(0)
	v_mul_u32_u24_e32 v2, 2, v2
	v_mul_u32_u24_e32 v3, 2, v3
	v_add_u32_e32 v5, 1, v5
	v_cmp_ne_u32_e32 vcc, v5, v2
	v_mov_b32_e32 v6, 0x2400
	s_cbranch_vccnz .Lxb1_poll
	buffer_wbl2 sc1
	s_waitcnt vmcnt(0)
	global_atomic_add v6, v1, s[98:99]


.LBB0_379:
	s_waitcnt vmcnt(0)
	s_waitcnt vmcnt(0)
	s_barrier
	s_mov_b64 s[0:1], exec
	v_readlane_b32 s2, v248, 3
	v_readlane_b32 s3, v248, 4
	s_and_b64 s[2:3], s[0:1], s[2:3]
	s_mov_b64 exec, s[2:3]
	s_cbranch_execz .LBB0_431
	v_readlane_b32 s98, v248, 1
	v_readlane_b32 s99, v248, 2
	v_mov_b32_e32 v0, 0x20ff0
	ds_read2_b32 v[2:3], v0 offset1:1
	v_mov_b32_e32 v1, 1
	v_mov_b32_e32 v4, s97
	v_lshlrev_b32_e32 v4, 8, v4
	s_add_u32 s98, s98, 0x1000
	s_addc_u32 s99, s99, 0
	s_nop 2
	global_atomic_add v5, v4, v1, s[98:99] offset:1024 sc0
	buffer_inv sc1
	s_waitcnt vmcnt(1) lgkmcnt(0)
	v_mul_u32_u24_e32 v2, 3, v2
	v_mul_u32_u24_e32 v3, 3, v3
	v_add_u32_e32 v5, 1, v5
	v_cmp_ne_u32_e32 vcc, v5, v2
	v_mov_b32_e32 v6, 0x2400
	s_cbranch_vccnz .Lxb2_poll
	buffer_wbl2 sc1
	s_waitcnt vmcnt(0)
	global_atomic_add v6, v1, s[98:99]


.Llt_p3_skip:
	s_waitcnt vmcnt(0)
	s_barrier
	s_mov_b64 s[0:1], exec
	v_readlane_b32 s2, v248, 3
	v_readlane_b32 s3, v248, 4
	s_and_b64 s[2:3], s[0:1], s[2:3]
	s_mov_b64 exec, s[2:3]
	s_cbranch_execz .LBB0_544
	v_readlane_b32 s98, v248, 1
	v_readlane_b32 s99, v248, 2
	v_mov_b32_e32 v0, 0x20ff0
	ds_read2_b32 v[2:3], v0 offset1:1
	v_mov_b32_e32 v1, 1
	v_mov_b32_e32 v4, s97
	v_lshlrev_b32_e32 v4, 8, v4
	s_add_u32 s98, s98, 0x1000
	s_addc_u32 s99, s99, 0
	s_nop 2
	global_atomic_add v5, v4, v1, s[98:99] offset:1024 sc0
	buffer_inv sc1
	s_waitcnt vmcnt(1) lgkmcnt(0)
	v_mul_u32_u24_e32 v2, 4, v2
	v_mul_u32_u24_e32 v3, 4, v3
	v_add_u32_e32 v5, 1, v5
	v_cmp_ne_u32_e32 vcc, v5, v2
	v_mov_b32_e32 v6, 0x2400
	s_cbranch_vccnz .Lxb3_poll
	buffer_wbl2 sc1
	s_waitcnt vmcnt(0)
	global_atomic_add v6, v1, s[98:99]


.LBB0_589:
	s_cmp_eq_u32 s101, 1
	s_cbranch_scc1 .Llt_p3_return
	s_waitcnt vmcnt(0)
	s_barrier
	s_and_saveexec_b64 s[0:1], s[80:81]
	s_cbranch_execz .LBB0_641
	v_readlane_b32 s98, v248, 1
	v_readlane_b32 s99, v248, 2
	v_mov_b32_e32 v0, 0x20ff0
	ds_read2_b32 v[2:3], v0 offset1:1
	v_mov_b32_e32 v1, 1
	v_mov_b32_e32 v4, s97
	v_lshlrev_b32_e32 v4, 8, v4
	s_add_u32 s98, s98, 0x1000
	s_addc_u32 s99, s99, 0
	s_nop 2
	global_atomic_add v5, v4, v1, s[98:99] offset:1024 sc0
	buffer_inv sc1
	s_waitcnt vmcnt(1) lgkmcnt(0)
	v_mul_u32_u24_e32 v2, 5, v2
	v_mul_u32_u24_e32 v3, 5, v3
	v_add_u32_e32 v5, 1, v5
	v_cmp_ne_u32_e32 vcc, v5, v2
	v_mov_b32_e32 v6, 0x2400
	s_cbranch_vccnz .Lxb4_poll
	buffer_wbl2 sc1
	s_waitcnt vmcnt(0)
	global_atomic_add v6, v1, s[98:99]


.LBB0_657:
	s_mov_b32 s6, s101
	s_waitcnt vmcnt(0)
	s_waitcnt vmcnt(0)
	s_barrier
	s_and_saveexec_b64 s[8:9], s[80:81]
	s_cbranch_execz .LBB0_709
	v_readlane_b32 s98, v248, 1
	v_readlane_b32 s99, v248, 2
	v_mov_b32_e32 v0, 0x20ff0
	ds_read2_b32 v[2:3], v0 offset1:1
	v_mov_b32_e32 v1, 1
	v_mov_b32_e32 v4, s97
	v_lshlrev_b32_e32 v4, 8, v4
	s_add_u32 s98, s98, 0x1000
	s_addc_u32 s99, s99, 0
	s_nop 2
	global_atomic_add v5, v4, v1, s[98:99] offset:1024 sc0
	buffer_inv sc1
	s_waitcnt vmcnt(1) lgkmcnt(0)
	v_mul_u32_u24_e32 v2, 6, v2
	v_mul_u32_u24_e32 v3, 6, v3
	v_add_u32_e32 v5, 1, v5
	v_cmp_ne_u32_e32 vcc, v5, v2
	v_mov_b32_e32 v6, 0x2400
	s_cbranch_vccnz .Lxb5_poll
	buffer_wbl2 sc1
	s_waitcnt vmcnt(0)
	global_atomic_add v6, v1, s[98:99]


.LBB0_733:
	s_waitcnt vmcnt(0)
	s_barrier
	s_and_saveexec_b64 s[0:1], s[80:81]
	s_cbranch_execz .LBB0_785
	v_readlane_b32 s98, v248, 1
	v_readlane_b32 s99, v248, 2
	v_mov_b32_e32 v0, 0x20ff0
	ds_read2_b32 v[2:3], v0 offset1:1
	v_mov_b32_e32 v1, 1
	v_mov_b32_e32 v4, s97
	v_lshlrev_b32_e32 v4, 8, v4
	s_add_u32 s98, s98, 0x1000
	s_addc_u32 s99, s99, 0
	s_nop 2
	global_atomic_add v5, v4, v1, s[98:99] offset:1024 sc0
	buffer_inv sc1
	s_waitcnt vmcnt(1) lgkmcnt(0)
	v_mul_u32_u24_e32 v2, 7, v2
	v_mul_u32_u24_e32 v3, 7, v3
	v_add_u32_e32 v5, 1, v5
	v_cmp_ne_u32_e32 vcc, v5, v2
	v_mov_b32_e32 v6, 0x2400
	s_cbranch_vccnz .Lxb6_poll
	buffer_wbl2 sc1
	s_waitcnt vmcnt(0)
	global_atomic_add v6, v1, s[98:99]


.LBB0_909:
	s_waitcnt vmcnt(0)
	s_barrier
	s_and_saveexec_b64 s[0:1], s[80:81]
	s_cbranch_execz .LBB0_961
	v_readlane_b32 s98, v248, 1
	v_readlane_b32 s99, v248, 2
	v_mov_b32_e32 v0, 0x20ff0
	ds_read2_b32 v[2:3], v0 offset1:1
	v_mov_b32_e32 v1, 1
	v_mov_b32_e32 v4, s97
	v_lshlrev_b32_e32 v4, 8, v4
	s_add_u32 s98, s98, 0x1000
	s_addc_u32 s99, s99, 0
	s_nop 2
	global_atomic_add v5, v4, v1, s[98:99] offset:1024 sc0
	buffer_inv sc1
	s_waitcnt vmcnt(1) lgkmcnt(0)
	v_mul_u32_u24_e32 v2, 8, v2
	v_mul_u32_u24_e32 v3, 8, v3
	v_add_u32_e32 v5, 1, v5
	v_cmp_ne_u32_e32 vcc, v5, v2
	v_mov_b32_e32 v6, 0x2400
	s_cbranch_vccnz .Lxb7_poll
	buffer_wbl2 sc1
	s_waitcnt vmcnt(0)
	global_atomic_add v6, v1, s[98:99]


.LBB0_985:
	s_waitcnt vmcnt(0)
	s_barrier
	s_and_saveexec_b64 s[0:1], s[80:81]
	s_cbranch_execz .LBB0_1037
	v_readlane_b32 s98, v248, 1
	v_readlane_b32 s99, v248, 2
	v_mov_b32_e32 v0, 0x20ff0
	ds_read2_b32 v[2:3], v0 offset1:1
	v_mov_b32_e32 v1, 1
	v_mov_b32_e32 v4, s97
	v_lshlrev_b32_e32 v4, 8, v4
	s_add_u32 s98, s98, 0x1000
	s_addc_u32 s99, s99, 0
	s_nop 2
	global_atomic_add v5, v4, v1, s[98:99] offset:1024 sc0
	buffer_inv sc1
	s_waitcnt vmcnt(1) lgkmcnt(0)
	v_mul_u32_u24_e32 v2, 9, v2
	v_mul_u32_u24_e32 v3, 9, v3
	v_add_u32_e32 v5, 1, v5
	v_cmp_ne_u32_e32 vcc, v5, v2
	v_mov_b32_e32 v6, 0x2400
	s_cbranch_vccnz .Lxb8_poll
	buffer_wbl2 sc1
	s_waitcnt vmcnt(0)
	global_atomic_add v6, v1, s[98:99]


.LBB0_1040:
	s_or_b64 exec, exec, s[24:25]
	s_waitcnt vmcnt(0)
	s_barrier
	s_and_saveexec_b64 s[0:1], s[80:81]
	s_cbranch_execz .LBB0_1092
	v_readlane_b32 s98, v248, 1
	v_readlane_b32 s99, v248, 2
	v_mov_b32_e32 v0, 0x20ff0
	ds_read2_b32 v[2:3], v0 offset1:1
	v_mov_b32_e32 v1, 1
	v_mov_b32_e32 v4, s97
	v_lshlrev_b32_e32 v4, 8, v4
	s_add_u32 s98, s98, 0x1000
	s_addc_u32 s99, s99, 0
	s_nop 2
	global_atomic_add v5, v4, v1, s[98:99] offset:1024 sc0
	buffer_inv sc1
	s_waitcnt vmcnt(1) lgkmcnt(0)
	v_mul_u32_u24_e32 v2, 10, v2
	v_mul_u32_u24_e32 v3, 10, v3
	v_add_u32_e32 v5, 1, v5
	v_cmp_ne_u32_e32 vcc, v5, v2
	v_mov_b32_e32 v6, 0x2400
	s_cbranch_vccnz .Lxb9_poll
	buffer_wbl2 sc1
	s_waitcnt vmcnt(0)
	global_atomic_add v6, v1, s[98:99]


.LBB0_1108:
	s_waitcnt vmcnt(0)
	s_waitcnt vmcnt(0)
	s_barrier
	s_and_saveexec_b64 s[0:1], s[80:81]
	s_cbranch_execz .LBB0_1160
	v_readlane_b32 s98, v248, 1
	v_readlane_b32 s99, v248, 2
	v_mov_b32_e32 v0, 0x20ff0
	ds_read2_b32 v[2:3], v0 offset1:1
	v_mov_b32_e32 v1, 1
	v_mov_b32_e32 v4, s97
	v_lshlrev_b32_e32 v4, 8, v4
	s_add_u32 s98, s98, 0x1000
	s_addc_u32 s99, s99, 0
	s_nop 2
	global_atomic_add v5, v4, v1, s[98:99] offset:1024 sc0
	buffer_inv sc1
	s_waitcnt vmcnt(1) lgkmcnt(0)
	v_mul_u32_u24_e32 v2, 11, v2
	v_mul_u32_u24_e32 v3, 11, v3
	v_add_u32_e32 v5, 1, v5
	v_cmp_ne_u32_e32 vcc, v5, v2
	v_mov_b32_e32 v6, 0x2400
	s_cbranch_vccnz .Lxb10_poll
	buffer_wbl2 sc1
	s_waitcnt vmcnt(0)
	global_atomic_add v6, v1, s[98:99]


.LBB0_1184:
	s_waitcnt vmcnt(0)
	s_barrier
	s_and_saveexec_b64 s[0:1], s[80:81]
	s_cbranch_execz .LBB0_1236
	v_readlane_b32 s98, v248, 1
	v_readlane_b32 s99, v248, 2
	v_mov_b32_e32 v0, 0x20ff0
	ds_read2_b32 v[2:3], v0 offset1:1
	v_mov_b32_e32 v1, 1
	v_mov_b32_e32 v4, s97
	v_lshlrev_b32_e32 v4, 8, v4
	s_add_u32 s98, s98, 0x1000
	s_addc_u32 s99, s99, 0
	s_nop 2
	global_atomic_add v5, v4, v1, s[98:99] offset:1024 sc0
	buffer_inv sc1
	s_waitcnt vmcnt(1) lgkmcnt(0)
	v_mul_u32_u24_e32 v2, 12, v2
	v_mul_u32_u24_e32 v3, 12, v3
	v_add_u32_e32 v5, 1, v5
	v_cmp_ne_u32_e32 vcc, v5, v2
	v_mov_b32_e32 v6, 0x2400
	s_cbranch_vccnz .Lxb11_poll
	buffer_wbl2 sc1
	s_waitcnt vmcnt(0)
	global_atomic_add v6, v1, s[98:99]

